# A-loop: bias init via 30 v_fmamk instead of 16 v_pk_fma, drop 8 v_mov_b64 copy (MFMA C!=D), hoist 4 K-frag ds_reads above bias math, drop compiler vmcnt(0)
# speedup vs baseline: 1.0089x; 1.0089x over previous
; DI f32x16 mfma(bf16x8 a, bf16x8 b, f32x16 c) { return __builtin_amdgcn_mfma_f32_32x32x16_bf16(a, b, c, 0, 0, 0); }
; DI void mask_causal(f32x16& s0, f32x16& s1, int dl) {
; #pragma unroll
;   for (int i = 0; i < 16; ++i) {
;     const int ci = (i & 3) + 8 * (i >> 2);
;     s0[i] = (ci <= dl) ? s0[i] : -INFINITY;
;     s1[i] = (ci + 32 <= dl) ? s1[i] : -INFINITY;
;   }
; }
; DI void diff_softmax_pv(const bf16x8 (&qf)[4], const u16* Ks, const u16* Vs, float& m, f32x4& ls0, f32x4& ls1, bf16x8 ones,
;                         f32x16 (&o)[2][2], float sl2, int dl, bool need_mask, bool first, int r, int h, int rs, const int (&lo)[4]) {
;     ...
;   const float nb = -sl2 * (float)dl - m;
; #pragma unroll
;   for (int i = 0; i < 16; ++i) {
;     const int ci = (i & 3) + 8 * (i >> 2);
;     b0[i] = fmaf(sl2, (float)ci, nb);
;     b1[i] = fmaf(sl2, (float)(ci + 32), nb);
;   }
;   {
;     __builtin_amdgcn_s_setprio(1);
;     f32x16 s0 = mfma(ldsv(Ks + lo[0]), qf[0], b0);
;     f32x16 s1 = mfma(ldsv(Ks + 32 * rs + lo[0]), qf[0], b1);
;     s0 = mfma(ldsv(Ks + lo[1]), qf[1], s0);
;     s1 = mfma(ldsv(Ks + 32 * rs + lo[1]), qf[1], s1);
;     __builtin_amdgcn_s_setprio(0);
;     if (need_mask) mask_causal(s0, s1, dl);
.LBB0_281:
	s_or_b64 exec, exec, s[2:3]
	v_cvt_f32_i32_e32 v66, v207
	s_and_b32 s2, s64, 0x2000
	v_lshl_add_u32 v211, s2, 1, v176
	v_lshl_add_u32 v213, v183, 1, v211
	v_lshl_add_u32 v212, v184, 1, v211
	v_fma_f32 v229, -v178, v66, -v204
	ds_read_b128 v[114:117], v213
	ds_read_b128 v[214:217], v213 offset:4096
	ds_read_b128 v[218:221], v212
	ds_read_b128 v[222:225], v212 offset:4096
	v_cmp_eq_u32_e64 s[38:39], 0, v208
	v_fma_f32 v66, 0, v178, v229
	v_add_f32_e32 v67, v178, v229
	v_fmamk_f32 v68, v178, 0x40000000, v229
	v_fmamk_f32 v69, v178, 0x40400000, v229
	v_fmamk_f32 v70, v178, 0x41000000, v229
	v_fmamk_f32 v71, v178, 0x41100000, v229
	v_fmamk_f32 v72, v178, 0x41200000, v229
	v_fmamk_f32 v73, v178, 0x41300000, v229
	v_fmamk_f32 v74, v178, 0x41800000, v229
	v_fmamk_f32 v75, v178, 0x41880000, v229
	v_fmamk_f32 v76, v178, 0x41900000, v229
	v_fmamk_f32 v77, v178, 0x41980000, v229
	v_fmamk_f32 v78, v178, 0x41c00000, v229
	v_fmamk_f32 v79, v178, 0x41c80000, v229
	v_fmamk_f32 v80, v178, 0x41d00000, v229
	v_fmamk_f32 v81, v178, 0x41d80000, v229
	v_fmamk_f32 v82, v178, 0x42000000, v229
	v_fmamk_f32 v83, v178, 0x42040000, v229
	v_fmamk_f32 v84, v178, 0x42080000, v229
	v_fmamk_f32 v85, v178, 0x420c0000, v229
	v_fmamk_f32 v86, v178, 0x42200000, v229
	v_fmamk_f32 v87, v178, 0x42240000, v229
	v_fmamk_f32 v88, v178, 0x42280000, v229
	v_fmamk_f32 v89, v178, 0x422c0000, v229
	v_fmamk_f32 v90, v178, 0x42400000, v229
	v_fmamk_f32 v91, v178, 0x42440000, v229
	v_fmamk_f32 v92, v178, 0x42480000, v229
	v_fmamk_f32 v93, v178, 0x424c0000, v229
	v_fmamk_f32 v94, v178, 0x42600000, v229
	v_fmamk_f32 v95, v178, 0x42640000, v229
	v_fmamk_f32 v96, v178, 0x42680000, v229
	v_fmamk_f32 v97, v178, 0x426c0000, v229
	s_setprio 1
	s_waitcnt lgkmcnt(2)
	v_mfma_f32_32x32x16_bf16 v[98:113], v[114:117], v[130:133], v[66:81]
	v_mfma_f32_32x32x16_bf16 v[114:129], v[214:217], v[130:133], v[82:97]
	s_waitcnt lgkmcnt(1)
	v_mfma_f32_32x32x16_bf16 v[98:113], v[218:221], v[134:137], v[98:113]
	s_waitcnt lgkmcnt(0)
	v_mfma_f32_32x32x16_bf16 v[114:129], v[222:225], v[134:137], v[114:129]
	s_setprio 0
	s_and_saveexec_b64 s[2:3], s[38:39]
	s_cbranch_execz .LBB0_283
	v_cmp_lt_i32_e32 vcc, -1, v207
	s_nop 4
	v_cndmask_b32_e32 v98, v199, v98, vcc
	v_cmp_lt_i32_e32 vcc, 31, v207
	s_nop 1
	v_cndmask_b32_e32 v114, v199, v114, vcc
	v_cmp_lt_i32_e32 vcc, 0, v207
	s_nop 1
	v_cndmask_b32_e32 v99, v199, v99, vcc
	v_cmp_lt_i32_e32 vcc, 32, v207
	s_nop 1
	v_cndmask_b32_e32 v115, v199, v115, vcc
	v_cmp_lt_i32_e32 vcc, 1, v207
	s_nop 1
	v_cndmask_b32_e32 v100, v199, v100, vcc
	v_cmp_lt_i32_e32 vcc, 33, v207
	s_nop 1
	v_cndmask_b32_e32 v116, v199, v116, vcc
	v_cmp_lt_i32_e32 vcc, 2, v207
	s_nop 1
	v_cndmask_b32_e32 v101, v199, v101, vcc
	v_cmp_lt_i32_e32 vcc, 34, v207
	s_nop 1
	v_cndmask_b32_e32 v117, v199, v117, vcc
	v_cmp_lt_i32_e32 vcc, 7, v207
	s_nop 1
	v_cndmask_b32_e32 v102, v199, v102, vcc
	v_cmp_lt_i32_e32 vcc, 39, v207
	s_nop 1
	v_cndmask_b32_e32 v118, v199, v118, vcc
	v_cmp_lt_i32_e32 vcc, 8, v207
	s_nop 1
	v_cndmask_b32_e32 v103, v199, v103, vcc
	v_cmp_lt_i32_e32 vcc, 40, v207
	s_nop 1
	v_cndmask_b32_e32 v119, v199, v119, vcc
	v_cmp_lt_i32_e32 vcc, 9, v207
	s_nop 1
	v_cndmask_b32_e32 v104, v199, v104, vcc
	v_cmp_lt_i32_e32 vcc, 41, v207
	s_nop 1
	v_cndmask_b32_e32 v120, v199, v120, vcc
	v_cmp_lt_i32_e32 vcc, 10, v207
	s_nop 1
	v_cndmask_b32_e32 v105, v199, v105, vcc
	v_cmp_lt_i32_e32 vcc, 42, v207
	s_nop 1
	v_cndmask_b32_e32 v121, v199, v121, vcc
	v_cmp_lt_i32_e32 vcc, 15, v207
	s_nop 1
	v_cndmask_b32_e32 v106, v199, v106, vcc
	v_cmp_lt_i32_e32 vcc, 47, v207
	s_nop 1
	v_cndmask_b32_e32 v122, v199, v122, vcc
	v_cmp_lt_i32_e32 vcc, 16, v207
	s_nop 1
	v_cndmask_b32_e32 v107, v199, v107, vcc
	v_cmp_lt_i32_e32 vcc, 48, v207
	s_nop 1
	v_cndmask_b32_e32 v123, v199, v123, vcc
	v_cmp_lt_i32_e32 vcc, 17, v207
	s_nop 1
	v_cndmask_b32_e32 v108, v199, v108, vcc
	v_cmp_lt_i32_e32 vcc, 49, v207
	s_nop 1
	v_cndmask_b32_e32 v124, v199, v124, vcc
	v_cmp_lt_i32_e32 vcc, 18, v207
	s_nop 1
	v_cndmask_b32_e32 v109, v199, v109, vcc
	v_cmp_lt_i32_e32 vcc, 50, v207
	s_nop 1
	v_cndmask_b32_e32 v125, v199, v125, vcc
	v_cmp_lt_i32_e32 vcc, 23, v207
	s_nop 1
	v_cndmask_b32_e32 v110, v199, v110, vcc
	v_cmp_lt_i32_e32 vcc, 55, v207
	s_nop 1
	v_cndmask_b32_e32 v126, v199, v126, vcc
	v_cmp_lt_i32_e32 vcc, 24, v207
	s_nop 1
	v_cndmask_b32_e32 v111, v199, v111, vcc
	v_cmp_lt_i32_e32 vcc, 56, v207
	s_nop 1
	v_cndmask_b32_e32 v127, v199, v127, vcc
	v_cmp_lt_i32_e32 vcc, 25, v207
	s_nop 1
	v_cndmask_b32_e32 v112, v199, v112, vcc
	v_cmp_lt_i32_e32 vcc, 57, v207
	s_nop 1
	v_cndmask_b32_e32 v128, v199, v128, vcc
	v_cmp_lt_i32_e32 vcc, 26, v207
	s_nop 1
	v_cndmask_b32_e32 v113, v199, v113, vcc
	v_cmp_lt_i32_e32 vcc, 58, v207
	s_nop 1
	v_cndmask_b32_e32 v129, v199, v129, vcc
